# v22 plus one static s_setprio 1 for waves 4-7 across the attention phase (reset at the phase-end barrier)
# speedup vs baseline: 1.0004x; 1.0004x over previous
; #define LAS __attribute__((address_space(3)))
; __device__ __forceinline__ unsigned pk2(float lo, float hi) { f32x2_t v = {lo, hi}; bf16x2_t b = __builtin_convertvector(v, bf16x2_t); return __builtin_bit_cast(unsigned, b); }
; __device__ __forceinline__ void attn_phase(const Frame& F, const float* relb, const bf16* QKV, const bf16* CK, const bf16* CV, bf16* O) {
;     ...
;     __syncthreads();
;     LAS unsigned char* const vtl = (LAS unsigned char*)F.lds + 32896 + F.wave * 9216;
;     LAS unsigned char* const qtl = (LAS unsigned char*)F.lds + 106624 + F.wave * 4608;
;     const int lane = F.lane, l31 = lane & 31, hh = lane >> 5;
;     const int i16 = lane & 15, q4 = i16 >> 2, p4 = i16 & 3, dblk = (lane >> 4) & 1;
;     const int gw = F.bid * 8 + F.wave, NGW = F.G * 8;
;     constexpr int NITEM = (32 * 32 + 32) * 32;
;     constexpr float C2 = 0.125f * LOG2E;
;     const int xw = (F.bid >> 3) * 8 + F.wave, xn = (F.G >> 3) * 8, xcd = F.bid & 7;
;     for (int jt = xw; jt < NITEM / 8; jt += xn) {
;         int lq_ = lane; asm volatile("" : "+v"(lq_));
;         LAS unsigned char* const wbase = vtl + (((lq_ >> 3) * 72 + 8 * (lq_ & 7)) * 2);
;         LAS unsigned char* const fbase = vtl + (((lq_ & 31) * 72 + 8 * (lq_ >> 5)) * 2);
;         LAS unsigned char* const qbase = qtl + (((lq_ & 31) * 72 + 8 * (lq_ >> 5)) * 2);
;         LAS unsigned char* const tbase = vtl + (((4 * (lq_ >> 5) + ((lq_ & 15) >> 2)) * 72 + 16 * ((lq_ >> 4) & 1) + 4 * (lq_ & 3)) * 2);
;         const bool smp = jt >= 4096; const int r0 = smp ? jt - 4096 : jt;
;         const int r = smp ? r0 : (r0 & ~255) | ((r0 + 10 * (r0 >> 8)) & 255);
;         const int qh = r & 1, c = smp ? 0 : (r >> 1) & 31, h = smp ? (r >> 1) & 15 : (r >> 6) & 15, b = xcd + 8 * (smp ? (r >> 5) : (r >> 10));
;     ...
;         const float inv = 1.0f / (lsum + __shfl_xor(lsum, 32));
;         bf16* orow = O + (qrow0 + l31) * D + h * 64 + 4 * hh;
; #pragma unroll
;         for (int i4 = 0; i4 < 4; ++i4) {
;             u32x2 w0; w0.x = pk2(o0[4 * i4] * inv, o0[4 * i4 + 1] * inv); w0.y = pk2(o0[4 * i4 + 2] * inv, o0[4 * i4 + 3] * inv); *(u32x2*)(orow + 8 * i4) = w0;
;             u32x2 w1; w1.x = pk2(o1[4 * i4] * inv, o1[4 * i4 + 1] * inv); w1.y = pk2(o1[4 * i4 + 2] * inv, o1[4 * i4 + 3] * inv); *(u32x2*)(orow + 32 + 8 * i4) = w1;
;         }
;     }
.LBB0_525:
	s_or_b64 exec, exec, s[0:1]
	v_readlane_b32 s0, v254, 38
	s_and_b32 s0, s0, -8
	s_add_i32 s22, s0, s67
	s_cmpk_lt_i32 s22, 0x1080
	s_waitcnt lgkmcnt(0)
	s_barrier
	v_readlane_b32 s1, v254, 39
	s_cbranch_scc0 .LBB0_560
	s_waitcnt vmcnt(16)
	v_lshlrev_b32_e32 v0, 3, v177
	v_and_b32_e32 v161, 56, v0
	v_readlane_b32 s0, v254, 40
	v_lshrrev_b32_e32 v156, 3, v177
	v_lshlrev_b32_e32 v0, 1, v161
	v_readlane_b32 s1, v254, 41
	v_lshl_add_u64 v[158:159], s[74:75], 0, v[0:1]
	v_mul_u32_u24_e32 v0, 0x48, v156
	v_cmp_lt_i32_e32 vcc, v228, v227
	s_and_b32 s23, s0, -8
	v_readlane_b32 s0, v254, 38
	v_and_b32_e32 v154, 31, v176
	v_and_b32_e32 v160, 4, v156
	v_add_lshl_u32 v0, v0, v161, 1
	s_waitcnt vmcnt(15)
	v_cndmask_b32_e32 v2, v232, v228, vcc
	s_and_b32 s24, s0, 7
	v_mov_b32_e32 v157, v1
	v_mov_b32_e32 v155, v1
	v_bitop3_b32 v175, v156, 4, v156 bitop3:0x3f
	v_or_b32_e32 v184, 2, v160
	v_or_b32_e32 v185, 3, v156
	v_or_b32_e32 v186, 8, v160
	v_or_b32_e32 v187, 9, v160
	v_or_b32_e32 v188, 10, v160
	v_or_b32_e32 v189, 11, v156
	v_or_b32_e32 v190, 16, v160
	v_or_b32_e32 v191, 17, v160
	v_or_b32_e32 v192, 18, v160
	v_or_b32_e32 v193, 19, v156
	v_or_b32_e32 v194, 24, v160
	v_or_b32_e32 v195, 25, v160
	v_or_b32_e32 v196, 26, v160
	v_or_b32_e32 v197, 27, v156
	v_lshlrev_b32_e32 v198, 2, v2
	v_sub_u32_e32 v199, v154, v160
	v_add_u32_e32 v200, s97, v0
	v_lshlrev_b32_e32 v162, 1, v160
	v_readlane_b32 s1, v254, 39
	s_cmp_ge_u32 s67, 4
	s_cbranch_scc0 .Lprio_att
	s_setprio 1
.Lprio_att:
	s_branch .LBB0_528
.LBB0_527:
	ds_bpermute_b32 v0, v198, v35
	v_lshl_add_u64 v[36:37], s[0:1], 0, v[154:155]
	v_lshlrev_b64 v[36:37], 11, v[36:37]
	s_mov_b32 s7, s51
	v_mov_b32_e32 v163, v1
	s_waitcnt lgkmcnt(0)
	v_add_f32_e32 v0, v35, v0
	v_div_scale_f32 v38, s[0:1], v0, v0, 1.0
	v_rcp_f32_e32 v39, v38
	v_readlane_b32 s0, v254, 48
	v_readlane_b32 s1, v254, 49
	s_add_i32 s22, s22, s23
	s_cmpk_gt_i32 s22, 0x107f
	v_lshl_add_u64 v[34:35], s[0:1], 0, v[36:37]
	v_fma_f32 v37, -v38, v39, 1.0
	v_div_scale_f32 v36, vcc, 1.0, v0, 1.0
	v_fmac_f32_e32 v39, v37, v39
	v_mul_f32_e32 v37, v36, v39
	v_fma_f32 v40, -v38, v37, v36
	v_fmac_f32_e32 v37, v40, v39
	v_fma_f32 v36, -v38, v37, v36
	v_div_fmas_f32 v36, v36, v39, v37
	v_div_fixup_f32 v0, v36, v0, 1.0
	v_lshl_add_u64 v[34:35], v[34:35], 0, s[6:7]
	v_pk_mul_f32 v[2:3], v[2:3], v[0:1] op_sel_hi:[1,0]
	v_pk_mul_f32 v[4:5], v[4:5], v[0:1] op_sel_hi:[1,0]
	v_lshl_add_u64 v[34:35], v[34:35], 0, v[162:163]
	v_cvt_pk_bf16_f32 v2, v2, v3
	v_cvt_pk_bf16_f32 v3, v4, v5
	global_store_dwordx2 v[34:35], v[2:3], off
	v_pk_mul_f32 v[2:3], v[18:19], v[0:1] op_sel_hi:[1,0]
	v_pk_mul_f32 v[4:5], v[20:21], v[0:1] op_sel_hi:[1,0]
	v_cvt_pk_bf16_f32 v2, v2, v3
	v_cvt_pk_bf16_f32 v3, v4, v5
	global_store_dwordx2 v[34:35], v[2:3], off offset:64
	v_pk_mul_f32 v[2:3], v[6:7], v[0:1] op_sel_hi:[1,0]
	v_pk_mul_f32 v[4:5], v[8:9], v[0:1] op_sel_hi:[1,0]
	v_cvt_pk_bf16_f32 v2, v2, v3
	v_cvt_pk_bf16_f32 v3, v4, v5
	global_store_dwordx2 v[34:35], v[2:3], off offset:16
	v_pk_mul_f32 v[2:3], v[22:23], v[0:1] op_sel_hi:[1,0]
	v_pk_mul_f32 v[4:5], v[24:25], v[0:1] op_sel_hi:[1,0]
	v_cvt_pk_bf16_f32 v2, v2, v3
	v_cvt_pk_bf16_f32 v3, v4, v5
	global_store_dwordx2 v[34:35], v[2:3], off offset:80
	v_pk_mul_f32 v[2:3], v[10:11], v[0:1] op_sel_hi:[1,0]
	v_pk_mul_f32 v[4:5], v[12:13], v[0:1] op_sel_hi:[1,0]
	v_cvt_pk_bf16_f32 v2, v2, v3
	v_cvt_pk_bf16_f32 v3, v4, v5
	global_store_dwordx2 v[34:35], v[2:3], off offset:32
	v_pk_mul_f32 v[2:3], v[26:27], v[0:1] op_sel_hi:[1,0]
	v_pk_mul_f32 v[4:5], v[28:29], v[0:1] op_sel_hi:[1,0]
	v_cvt_pk_bf16_f32 v2, v2, v3
	v_cvt_pk_bf16_f32 v3, v4, v5
	global_store_dwordx2 v[34:35], v[2:3], off offset:96
	v_pk_mul_f32 v[2:3], v[14:15], v[0:1] op_sel_hi:[1,0]
	v_pk_mul_f32 v[4:5], v[16:17], v[0:1] op_sel_hi:[1,0]
	v_cvt_pk_bf16_f32 v2, v2, v3
	v_cvt_pk_bf16_f32 v3, v4, v5
	global_store_dwordx2 v[34:35], v[2:3], off offset:48
	v_pk_mul_f32 v[2:3], v[30:31], v[0:1] op_sel_hi:[1,0]
	v_pk_mul_f32 v[4:5], v[32:33], v[0:1] op_sel_hi:[1,0]
	v_cvt_pk_bf16_f32 v2, v2, v3
	v_cvt_pk_bf16_f32 v3, v4, v5
	global_store_dwordx2 v[34:35], v[2:3], off offset:112
	s_cbranch_scc1 .LBB0_560

; __device__ __forceinline__ int lane_id_() { return (int)__builtin_amdgcn_mbcnt_hi(~0u, __builtin_amdgcn_mbcnt_lo(~0u, 0u)); }
; #define LAS __attribute__((address_space(3)))
; __device__ __forceinline__ unsigned xb_xcc_id() { return (unsigned)__builtin_amdgcn_s_getreg((3 << 11) | 20) & 0xFu; }
; __device__ __forceinline__ void xcd_barrier(const XcdBarrier& b) {
;     asm volatile("s_waitcnt vmcnt(0)" ::: "memory");
;     __syncthreads();
;     if (b.w0 == 0 && lane_id_() == 0) {
;         unsigned* bar = b.bar;
;         __builtin_amdgcn_s_waitcnt(0);
;         unsigned nloc = b.st[0], nx = b.st[1];
;         if (nloc == 0u) { xcd_barrier_complete(bar, b.x, nloc, nx); b.st[0] = nloc; b.st[1] = nx; }
; __global__ void __launch_bounds__(512, 2) fwd_megakernel(Args a) {
;     ...
;         if (ph == 0 && a.ph_hi > 1) grid.sync();
;         else if (ph + 1 < a.ph_hi) { XcdBarrier xb_; xb_.w0 = F.wave; xb_.bar = (unsigned*)AIN(24); xb_.x = xb_xcc_id(); xb_.st = (volatile LAS unsigned*)(glds + (LDS_BYTES - 16)); xcd_barrier(xb_); }
.LBB0_741:
	s_setprio 0
	s_cmp_lg_u32 s24, 0
	v_readlane_b32 s4, v254, 29
	s_cselect_b64 s[2:3], -1, 0
	v_readlane_b32 s5, v254, 30
	s_or_b64 s[4:5], s[2:3], s[4:5]
	s_mov_b64 s[0:1], -1
	s_mov_b64 s[2:3], 0
	s_and_b64 vcc, exec, s[4:5]
	s_cbranch_vccz .LBB0_796
	s_add_i32 s2, s24, 1
	s_mov_b64 s[0:1], 0
	s_cmp_lt_i32 s2, s25
	s_mov_b64 s[2:3], 0
	s_cbranch_scc0 .LBB0_796
	s_waitcnt lgkmcnt(0)
	s_getreg_b32 s6, hwreg(HW_REG_XCC_ID, 0, 4)
	s_waitcnt vmcnt(0)
	v_readlane_b32 s2, v254, 17
	v_cmp_eq_u32_e32 vcc, 0, v232
	v_readlane_b32 s3, v254, 18
	s_and_b64 s[4:5], s[2:3], vcc
	s_waitcnt vmcnt(0)
	s_barrier
	s_and_saveexec_b64 s[2:3], s[4:5]
	s_cbranch_execz .LBB0_795
	v_readlane_b32 s7, v254, 31
	s_load_dwordx2 s[4:5], s[88:89], 0xc0
	s_waitcnt vmcnt(0) expcnt(0) lgkmcnt(0)
	v_mov_b32_e32 v0, s7
	ds_read_b32 v3, v0
	v_readlane_b32 s7, v254, 32
	s_and_b32 s20, s6, 15
	s_waitcnt lgkmcnt(0)
	v_cmp_ne_u32_e32 vcc, 0, v3
	v_mov_b32_e32 v0, s7
	ds_read_b32 v2, v0
	s_cbranch_vccnz .LBB0_759
	s_add_u32 s6, s4, 0x1000
	s_addc_u32 s7, s5, 0
	s_add_u32 s8, s4, 0x1100
	s_addc_u32 s9, s5, 0
	s_add_u32 s10, s4, 0x1200
	s_addc_u32 s11, s5, 0
	s_add_u32 s12, s4, 0x1300
	s_addc_u32 s13, s5, 0
	s_mov_b32 s21, 1
	s_branch .LBB0_747
